# v96 + ph_post1: hand-written gate epilogue (gate loads pipelined 4 rows deep instead of 4 serialized load groups, packed f32 math, same op order)
# speedup vs baseline: 1.0080x; 1.0030x over previous
; DI float bflo(unsigned u) { return __uint_as_float(u << 16); }
;     DI void operator()(const f32x4 (&acc)[2][2][4][2], const Unit& u, int wr, int wc, int fr, int fq) const {
;         const int col0 = u.pn * BM + wc * 32 + 8 * fq;
;         const int rowb = u.pm * BM + wr * 64 + fr;
;         f32x4 bb[2][2];
; #pragma unroll
;         for (int bj = 0; bj < 2; ++bj) { bb[bj][0] = *(const f32x4*)(bg + col0 + bj * HALF); bb[bj][1] = *(const f32x4*)(bg + col0 + bj * HALF + 4); }
; #pragma unroll
;         for (int ai = 0; ai < 2; ++ai)
; #pragma unroll
;             for (int mp = 0; mp < 2; ++mp) {
;                 u32x4 zg[2][2], yv[2][2];
; #pragma unroll
;                 for (int mm = 0; mm < 2; ++mm)
; #pragma unroll
;                     for (int bj = 0; bj < 2; ++bj) { const int row = rowb + ai * HALF + (2 * mp + mm) * 16, col = col0 + bj * HALF;
;                         zg[mm][bj] = *(const u32x4*)(Zg + (size_t)row * INW + col);
;                         if (SECOND) yv[mm][bj] = *(const u32x4*)(Y1 + (size_t)row * D + col); }
;                 asm volatile("" ::: "memory");
; #pragma unroll
;                 for (int mm = 0; mm < 2; ++mm)
; #pragma unroll
;                     for (int bj = 0; bj < 2; ++bj) { const int m = 2 * mp + mm; const int row = rowb + ai * HALF + m * 16, col = col0 + bj * HALF;
;                         const u32x4 z = zg[mm][bj]; const f32x4 b0 = bb[bj][0], b1 = bb[bj][1];
;                         f32x4 g0, g1;
;                         g0[0] = fsigmoid(bflo(z.x) + b0[0]); g0[1] = fsigmoid(bfhi(z.x) + b0[1]); g0[2] = fsigmoid(bflo(z.y) + b0[2]); g0[3] = fsigmoid(bfhi(z.y) + b0[3]);
;                         g1[0] = fsigmoid(bflo(z.z) + b1[0]); g1[1] = fsigmoid(bfhi(z.z) + b1[1]); g1[2] = fsigmoid(bflo(z.w) + b1[2]); g1[3] = fsigmoid(bfhi(z.w) + b1[3]);
;                         f32x4 v0 = g0 * acc[ai][bj][m][0], v1 = g1 * acc[ai][bj][m][1];
;                         if (SECOND) { const u32x4 y = yv[mm][bj];
;                             v0[0] += bflo(y.x); v0[1] += bfhi(y.x); v0[2] += bflo(y.y); v0[3] += bfhi(y.y); v1[0] += bflo(y.z); v1[1] += bfhi(y.z); v1[2] += bflo(y.w); v1[3] += bfhi(y.w); }
;                         u32x4 w; w.x = pk2(v0[0], v0[1]); w.y = pk2(v0[2], v0[3]); w.z = pk2(v1[0], v1[1]); w.w = pk2(v1[2], v1[3]);
;                         *(u32x4*)((SECOND ? Mb : Y1) + (size_t)row * D + col) = w; }
.LBB0_518:
	v_lshl_or_b32 v233, s17, 8, v181
	v_lshl_add_u32 v232, s62, 8, v1
	v_lshlrev_b32_e32 v237, 2, v233
	v_mul_lo_u32 v234, v232, s78
	global_load_dwordx4 v[138:141], v237, s[48:49]
	global_load_dwordx4 v[142:145], v237, s[48:49] offset:16
	global_load_dwordx4 v[154:157], v237, s[48:49] offset:512
	global_load_dwordx4 v[170:173], v237, s[48:49] offset:528
	v_lshl_add_u32 v234, v233, 1, v234
	v_mov_b32_e32 v206, v234
	global_load_dwordx4 v[206:209], v206, s[8:9]
	v_mov_b32_e32 v210, v234
	global_load_dwordx4 v[210:213], v210, s[8:9] offset:256
	v_add_u32_e32 v214, 0x4c000, v234
	global_load_dwordx4 v[214:217], v214, s[8:9]
	v_add_u32_e32 v218, 0x4c000, v234
	global_load_dwordx4 v[218:221], v218, s[8:9] offset:256
	v_add_u32_e32 v200, 0x98000, v234
	global_load_dwordx4 v[200:203], v200, s[8:9]
	v_add_u32_e32 v184, 0x98000, v234
	global_load_dwordx4 v[184:187], v184, s[8:9] offset:256
	v_add_u32_e32 v188, 0xe4000, v234
	global_load_dwordx4 v[188:191], v188, s[8:9]
	v_add_u32_e32 v174, 0xe4000, v234
	global_load_dwordx4 v[174:177], v174, s[8:9] offset:256
	v_lshlrev_b32_e32 v235, 11, v232
	s_mov_b32 s98, 0xbfb8aa3b
	s_mov_b32 s100, 1.0
	v_lshl_add_u32 v235, v233, 1, v235
	s_waitcnt vmcnt(6)
	v_lshlrev_b32_e32 v58, 16, v206
	v_and_b32_e32 v59, 0xffff0000, v206
	v_lshlrev_b32_e32 v60, 16, v207
	v_and_b32_e32 v61, 0xffff0000, v207
	v_lshlrev_b32_e32 v62, 16, v208
	v_and_b32_e32 v63, 0xffff0000, v208
	v_lshlrev_b32_e32 v64, 16, v209
	v_and_b32_e32 v65, 0xffff0000, v209
	v_pk_add_f32 v[58:59], v[138:139], v[58:59]
	v_pk_add_f32 v[60:61], v[140:141], v[60:61]
	v_pk_add_f32 v[62:63], v[142:143], v[62:63]
	v_pk_add_f32 v[64:65], v[144:145], v[64:65]
	v_pk_mul_f32 v[58:59], v[58:59], s[98:99] op_sel_hi:[1,0]
	v_pk_mul_f32 v[60:61], v[60:61], s[98:99] op_sel_hi:[1,0]
	v_pk_mul_f32 v[62:63], v[62:63], s[98:99] op_sel_hi:[1,0]
	v_pk_mul_f32 v[64:65], v[64:65], s[98:99] op_sel_hi:[1,0]
	v_exp_f32_e32 v58, v58
	v_exp_f32_e32 v59, v59
	v_exp_f32_e32 v60, v60
	v_exp_f32_e32 v61, v61
	v_exp_f32_e32 v62, v62
	v_exp_f32_e32 v63, v63
	v_exp_f32_e32 v64, v64
	v_exp_f32_e32 v65, v65
	v_pk_add_f32 v[58:59], v[58:59], s[100:101] op_sel_hi:[1,0]
	v_pk_add_f32 v[60:61], v[60:61], s[100:101] op_sel_hi:[1,0]
	v_pk_add_f32 v[62:63], v[62:63], s[100:101] op_sel_hi:[1,0]
	v_pk_add_f32 v[64:65], v[64:65], s[100:101] op_sel_hi:[1,0]
	v_rcp_f32_e32 v58, v58
	v_rcp_f32_e32 v59, v59
	v_rcp_f32_e32 v60, v60
	v_rcp_f32_e32 v61, v61
	v_rcp_f32_e32 v62, v62
	v_rcp_f32_e32 v63, v63
	v_rcp_f32_e32 v64, v64
	v_rcp_f32_e32 v65, v65
	v_pk_mul_f32 v[150:151], v[150:151], v[58:59]
	v_pk_mul_f32 v[152:153], v[152:153], v[60:61]
	v_pk_mul_f32 v[146:147], v[146:147], v[62:63]
	v_pk_mul_f32 v[148:149], v[148:149], v[64:65]
	v_cvt_pk_bf16_f32 v42, v150, v151
	v_cvt_pk_bf16_f32 v43, v152, v153
	v_cvt_pk_bf16_f32 v44, v146, v147
	v_cvt_pk_bf16_f32 v45, v148, v149
	v_lshlrev_b32_e32 v58, 16, v210
	v_and_b32_e32 v59, 0xffff0000, v210
	v_lshlrev_b32_e32 v60, 16, v211
	v_and_b32_e32 v61, 0xffff0000, v211
	v_lshlrev_b32_e32 v62, 16, v212
	v_and_b32_e32 v63, 0xffff0000, v212
	v_lshlrev_b32_e32 v64, 16, v213
	v_and_b32_e32 v65, 0xffff0000, v213
	v_pk_add_f32 v[58:59], v[154:155], v[58:59]
	v_pk_add_f32 v[60:61], v[156:157], v[60:61]
	v_pk_add_f32 v[62:63], v[170:171], v[62:63]
	v_pk_add_f32 v[64:65], v[172:173], v[64:65]
	v_pk_mul_f32 v[58:59], v[58:59], s[98:99] op_sel_hi:[1,0]
	v_pk_mul_f32 v[60:61], v[60:61], s[98:99] op_sel_hi:[1,0]
	v_pk_mul_f32 v[62:63], v[62:63], s[98:99] op_sel_hi:[1,0]
	v_pk_mul_f32 v[64:65], v[64:65], s[98:99] op_sel_hi:[1,0]
	v_exp_f32_e32 v58, v58
	v_exp_f32_e32 v59, v59
	v_exp_f32_e32 v60, v60
	v_exp_f32_e32 v61, v61
	v_exp_f32_e32 v62, v62
	v_exp_f32_e32 v63, v63
	v_exp_f32_e32 v64, v64
	v_exp_f32_e32 v65, v65
	v_pk_add_f32 v[58:59], v[58:59], s[100:101] op_sel_hi:[1,0]
	v_pk_add_f32 v[60:61], v[60:61], s[100:101] op_sel_hi:[1,0]
	v_pk_add_f32 v[62:63], v[62:63], s[100:101] op_sel_hi:[1,0]
	v_pk_add_f32 v[64:65], v[64:65], s[100:101] op_sel_hi:[1,0]
	v_rcp_f32_e32 v58, v58
	v_rcp_f32_e32 v59, v59
	v_rcp_f32_e32 v60, v60
	v_rcp_f32_e32 v61, v61
	v_rcp_f32_e32 v62, v62
	v_rcp_f32_e32 v63, v63
	v_rcp_f32_e32 v64, v64
	v_rcp_f32_e32 v65, v65
	v_pk_mul_f32 v[134:135], v[134:135], v[58:59]
	v_pk_mul_f32 v[136:137], v[136:137], v[60:61]
	v_pk_mul_f32 v[130:131], v[130:131], v[62:63]
	v_pk_mul_f32 v[132:133], v[132:133], v[64:65]
	v_cvt_pk_bf16_f32 v46, v134, v135
	v_cvt_pk_bf16_f32 v47, v136, v137
	v_cvt_pk_bf16_f32 v48, v130, v131
	v_cvt_pk_bf16_f32 v49, v132, v133
	v_add_u32_e32 v206, 0x260000, v234
	global_load_dwordx4 v[206:209], v206, s[8:9]
	v_add_u32_e32 v210, 0x260000, v234
	global_load_dwordx4 v[210:213], v210, s[8:9] offset:256
	global_store_dwordx4 v235, v[42:45], s[50:51]
	global_store_dwordx4 v235, v[46:49], s[50:51] offset:256
	s_waitcnt vmcnt(8)
; DI unsigned pk2(float lo, float hi) { unsigned r; asm("v_cvt_pk_bf16_f32 %0, %1, %2" : "=v"(r) : "v"(lo), "v"(hi)); return r; }
; DI float bflo(unsigned u) { return __uint_as_float(u << 16); }
; DI float bfhi(unsigned u) { return __uint_as_float(u & 0xffff0000u); }
; DI float fsigmoid(float x) { return frcp(1.0f + fexp2(-1.44269504f * x)); }
;     DI void operator()(const f32x4 (&acc)[2][2][4][2], const Unit& u, int wr, int wc, int fr, int fq) const {
;     ...
;                     for (int bj = 0; bj < 2; ++bj) { const int row = rowb + ai * HALF + (2 * mp + mm) * 16, col = col0 + bj * HALF;
;                         zg[mm][bj] = *(const u32x4*)(Zg + (size_t)row * INW + col);
;                         if (SECOND) yv[mm][bj] = *(const u32x4*)(Y1 + (size_t)row * D + col); }
;                 asm volatile("" ::: "memory");
; #pragma unroll
;                 for (int mm = 0; mm < 2; ++mm)
; #pragma unroll
;                     for (int bj = 0; bj < 2; ++bj) { const int m = 2 * mp + mm; const int row = rowb + ai * HALF + m * 16, col = col0 + bj * HALF;
;                         const u32x4 z = zg[mm][bj]; const f32x4 b0 = bb[bj][0], b1 = bb[bj][1];
;                         f32x4 g0, g1;
;                         g0[0] = fsigmoid(bflo(z.x) + b0[0]); g0[1] = fsigmoid(bfhi(z.x) + b0[1]); g0[2] = fsigmoid(bflo(z.y) + b0[2]); g0[3] = fsigmoid(bfhi(z.y) + b0[3]);
;                         g1[0] = fsigmoid(bflo(z.z) + b1[0]); g1[1] = fsigmoid(bfhi(z.z) + b1[1]); g1[2] = fsigmoid(bflo(z.w) + b1[2]); g1[3] = fsigmoid(bfhi(z.w) + b1[3]);
;                         f32x4 v0 = g0 * acc[ai][bj][m][0], v1 = g1 * acc[ai][bj][m][1];
;                         if (SECOND) { const u32x4 y = yv[mm][bj];
;                             v0[0] += bflo(y.x); v0[1] += bfhi(y.x); v0[2] += bflo(y.y); v0[3] += bfhi(y.y); v1[0] += bflo(y.z); v1[1] += bfhi(y.z); v1[2] += bflo(y.w); v1[3] += bfhi(y.w); }
;                         u32x4 w; w.x = pk2(v0[0], v0[1]); w.y = pk2(v0[2], v0[3]); w.z = pk2(v1[0], v1[1]); w.w = pk2(v1[2], v1[3]);
;                         *(u32x4*)((SECOND ? Mb : Y1) + (size_t)row * D + col) = w; }
	v_lshlrev_b32_e32 v58, 16, v214
	v_and_b32_e32 v59, 0xffff0000, v214
	v_lshlrev_b32_e32 v60, 16, v215
	v_and_b32_e32 v61, 0xffff0000, v215
	v_lshlrev_b32_e32 v62, 16, v216
	v_and_b32_e32 v63, 0xffff0000, v216
	v_lshlrev_b32_e32 v64, 16, v217
	v_and_b32_e32 v65, 0xffff0000, v217
	v_pk_add_f32 v[58:59], v[138:139], v[58:59]
	v_pk_add_f32 v[60:61], v[140:141], v[60:61]
	v_pk_add_f32 v[62:63], v[142:143], v[62:63]
	v_pk_add_f32 v[64:65], v[144:145], v[64:65]
	v_pk_mul_f32 v[58:59], v[58:59], s[98:99] op_sel_hi:[1,0]
	v_pk_mul_f32 v[60:61], v[60:61], s[98:99] op_sel_hi:[1,0]
	v_pk_mul_f32 v[62:63], v[62:63], s[98:99] op_sel_hi:[1,0]
	v_pk_mul_f32 v[64:65], v[64:65], s[98:99] op_sel_hi:[1,0]
	v_exp_f32_e32 v58, v58
	v_exp_f32_e32 v59, v59
	v_exp_f32_e32 v60, v60
	v_exp_f32_e32 v61, v61
	v_exp_f32_e32 v62, v62
	v_exp_f32_e32 v63, v63
	v_exp_f32_e32 v64, v64
	v_exp_f32_e32 v65, v65
	v_pk_add_f32 v[58:59], v[58:59], s[100:101] op_sel_hi:[1,0]
	v_pk_add_f32 v[60:61], v[60:61], s[100:101] op_sel_hi:[1,0]
	v_pk_add_f32 v[62:63], v[62:63], s[100:101] op_sel_hi:[1,0]
	v_pk_add_f32 v[64:65], v[64:65], s[100:101] op_sel_hi:[1,0]
	v_rcp_f32_e32 v58, v58
	v_rcp_f32_e32 v59, v59
	v_rcp_f32_e32 v60, v60
	v_rcp_f32_e32 v61, v61
	v_rcp_f32_e32 v62, v62
	v_rcp_f32_e32 v63, v63
	v_rcp_f32_e32 v64, v64
	v_rcp_f32_e32 v65, v65
	v_pk_mul_f32 v[126:127], v[126:127], v[58:59]
	v_pk_mul_f32 v[128:129], v[128:129], v[60:61]
	v_pk_mul_f32 v[122:123], v[122:123], v[62:63]
	v_pk_mul_f32 v[124:125], v[124:125], v[64:65]
	v_cvt_pk_bf16_f32 v42, v126, v127
	v_cvt_pk_bf16_f32 v43, v128, v129
	v_cvt_pk_bf16_f32 v44, v122, v123
	v_cvt_pk_bf16_f32 v45, v124, v125
	v_lshlrev_b32_e32 v58, 16, v218
	v_and_b32_e32 v59, 0xffff0000, v218
	v_lshlrev_b32_e32 v60, 16, v219
	v_and_b32_e32 v61, 0xffff0000, v219
	v_lshlrev_b32_e32 v62, 16, v220
	v_and_b32_e32 v63, 0xffff0000, v220
	v_lshlrev_b32_e32 v64, 16, v221
	v_and_b32_e32 v65, 0xffff0000, v221
	v_pk_add_f32 v[58:59], v[154:155], v[58:59]
	v_pk_add_f32 v[60:61], v[156:157], v[60:61]
	v_pk_add_f32 v[62:63], v[170:171], v[62:63]
	v_pk_add_f32 v[64:65], v[172:173], v[64:65]
	v_pk_mul_f32 v[58:59], v[58:59], s[98:99] op_sel_hi:[1,0]
	v_pk_mul_f32 v[60:61], v[60:61], s[98:99] op_sel_hi:[1,0]
	v_pk_mul_f32 v[62:63], v[62:63], s[98:99] op_sel_hi:[1,0]
	v_pk_mul_f32 v[64:65], v[64:65], s[98:99] op_sel_hi:[1,0]
	v_exp_f32_e32 v58, v58
	v_exp_f32_e32 v59, v59
	v_exp_f32_e32 v60, v60
	v_exp_f32_e32 v61, v61
	v_exp_f32_e32 v62, v62
	v_exp_f32_e32 v63, v63
	v_exp_f32_e32 v64, v64
	v_exp_f32_e32 v65, v65
	v_pk_add_f32 v[58:59], v[58:59], s[100:101] op_sel_hi:[1,0]
	v_pk_add_f32 v[60:61], v[60:61], s[100:101] op_sel_hi:[1,0]
	v_pk_add_f32 v[62:63], v[62:63], s[100:101] op_sel_hi:[1,0]
	v_pk_add_f32 v[64:65], v[64:65], s[100:101] op_sel_hi:[1,0]
	v_rcp_f32_e32 v58, v58
	v_rcp_f32_e32 v59, v59
	v_rcp_f32_e32 v60, v60
	v_rcp_f32_e32 v61, v61
	v_rcp_f32_e32 v62, v62
	v_rcp_f32_e32 v63, v63
	v_rcp_f32_e32 v64, v64
	v_rcp_f32_e32 v65, v65
	v_pk_mul_f32 v[118:119], v[118:119], v[58:59]
	v_pk_mul_f32 v[120:121], v[120:121], v[60:61]
	v_pk_mul_f32 v[114:115], v[114:115], v[62:63]
	v_pk_mul_f32 v[116:117], v[116:117], v[64:65]
	v_cvt_pk_bf16_f32 v46, v118, v119
	v_cvt_pk_bf16_f32 v47, v120, v121
	v_cvt_pk_bf16_f32 v48, v114, v115
	v_cvt_pk_bf16_f32 v49, v116, v117
	v_add_u32_e32 v214, 0x2ac000, v234
	global_load_dwordx4 v[214:217], v214, s[8:9]
	v_add_u32_e32 v218, 0x2ac000, v234
	global_load_dwordx4 v[218:221], v218, s[8:9] offset:256
	v_add_u32_e32 v236, 0x8000, v235
	global_store_dwordx4 v236, v[42:45], s[50:51]
	global_store_dwordx4 v236, v[46:49], s[50:51] offset:256
	s_waitcnt vmcnt(10)
	v_lshlrev_b32_e32 v58, 16, v200
	v_and_b32_e32 v59, 0xffff0000, v200
	v_lshlrev_b32_e32 v60, 16, v201
	v_and_b32_e32 v61, 0xffff0000, v201
	v_lshlrev_b32_e32 v62, 16, v202
	v_and_b32_e32 v63, 0xffff0000, v202
	v_lshlrev_b32_e32 v64, 16, v203
	v_and_b32_e32 v65, 0xffff0000, v203
	v_pk_add_f32 v[58:59], v[138:139], v[58:59]
	v_pk_add_f32 v[60:61], v[140:141], v[60:61]
	v_pk_add_f32 v[62:63], v[142:143], v[62:63]
	v_pk_add_f32 v[64:65], v[144:145], v[64:65]
	v_pk_mul_f32 v[58:59], v[58:59], s[98:99] op_sel_hi:[1,0]
	v_pk_mul_f32 v[60:61], v[60:61], s[98:99] op_sel_hi:[1,0]
	v_pk_mul_f32 v[62:63], v[62:63], s[98:99] op_sel_hi:[1,0]
	v_pk_mul_f32 v[64:65], v[64:65], s[98:99] op_sel_hi:[1,0]
	v_exp_f32_e32 v58, v58
	v_exp_f32_e32 v59, v59
	v_exp_f32_e32 v60, v60
	v_exp_f32_e32 v61, v61
	v_exp_f32_e32 v62, v62
	v_exp_f32_e32 v63, v63
	v_exp_f32_e32 v64, v64
	v_exp_f32_e32 v65, v65
	v_pk_add_f32 v[58:59], v[58:59], s[100:101] op_sel_hi:[1,0]
	v_pk_add_f32 v[60:61], v[60:61], s[100:101] op_sel_hi:[1,0]
	v_pk_add_f32 v[62:63], v[62:63], s[100:101] op_sel_hi:[1,0]
	v_pk_add_f32 v[64:65], v[64:65], s[100:101] op_sel_hi:[1,0]
	v_rcp_f32_e32 v58, v58
	v_rcp_f32_e32 v59, v59
	v_rcp_f32_e32 v60, v60
	v_rcp_f32_e32 v61, v61
	v_rcp_f32_e32 v62, v62
	v_rcp_f32_e32 v63, v63
	v_rcp_f32_e32 v64, v64
	v_rcp_f32_e32 v65, v65
	v_pk_mul_f32 v[110:111], v[110:111], v[58:59]
	v_pk_mul_f32 v[112:113], v[112:113], v[60:61]
	v_pk_mul_f32 v[106:107], v[106:107], v[62:63]
	v_pk_mul_f32 v[108:109], v[108:109], v[64:65]
	v_cvt_pk_bf16_f32 v42, v110, v111
	v_cvt_pk_bf16_f32 v43, v112, v113
	v_cvt_pk_bf16_f32 v44, v106, v107
	v_cvt_pk_bf16_f32 v45, v108, v109
	v_lshlrev_b32_e32 v58, 16, v184
	v_and_b32_e32 v59, 0xffff0000, v184
	v_lshlrev_b32_e32 v60, 16, v185
	v_and_b32_e32 v61, 0xffff0000, v185
	v_lshlrev_b32_e32 v62, 16, v186
	v_and_b32_e32 v63, 0xffff0000, v186
	v_lshlrev_b32_e32 v64, 16, v187
	v_and_b32_e32 v65, 0xffff0000, v187
	v_pk_add_f32 v[58:59], v[154:155], v[58:59]
	v_pk_add_f32 v[60:61], v[156:157], v[60:61]
; DI unsigned pk2(float lo, float hi) { unsigned r; asm("v_cvt_pk_bf16_f32 %0, %1, %2" : "=v"(r) : "v"(lo), "v"(hi)); return r; }
; DI float bflo(unsigned u) { return __uint_as_float(u << 16); }
; DI float bfhi(unsigned u) { return __uint_as_float(u & 0xffff0000u); }
; DI float fsigmoid(float x) { return frcp(1.0f + fexp2(-1.44269504f * x)); }
;     DI void operator()(const f32x4 (&acc)[2][2][4][2], const Unit& u, int wr, int wc, int fr, int fq) const {
;     ...
;                     for (int bj = 0; bj < 2; ++bj) { const int row = rowb + ai * HALF + (2 * mp + mm) * 16, col = col0 + bj * HALF;
;                         zg[mm][bj] = *(const u32x4*)(Zg + (size_t)row * INW + col);
;                         if (SECOND) yv[mm][bj] = *(const u32x4*)(Y1 + (size_t)row * D + col); }
;                 asm volatile("" ::: "memory");
; #pragma unroll
;                 for (int mm = 0; mm < 2; ++mm)
; #pragma unroll
;                     for (int bj = 0; bj < 2; ++bj) { const int m = 2 * mp + mm; const int row = rowb + ai * HALF + m * 16, col = col0 + bj * HALF;
;                         const u32x4 z = zg[mm][bj]; const f32x4 b0 = bb[bj][0], b1 = bb[bj][1];
;                         f32x4 g0, g1;
;                         g0[0] = fsigmoid(bflo(z.x) + b0[0]); g0[1] = fsigmoid(bfhi(z.x) + b0[1]); g0[2] = fsigmoid(bflo(z.y) + b0[2]); g0[3] = fsigmoid(bfhi(z.y) + b0[3]);
;                         g1[0] = fsigmoid(bflo(z.z) + b1[0]); g1[1] = fsigmoid(bfhi(z.z) + b1[1]); g1[2] = fsigmoid(bflo(z.w) + b1[2]); g1[3] = fsigmoid(bfhi(z.w) + b1[3]);
;                         f32x4 v0 = g0 * acc[ai][bj][m][0], v1 = g1 * acc[ai][bj][m][1];
;                         if (SECOND) { const u32x4 y = yv[mm][bj];
;                             v0[0] += bflo(y.x); v0[1] += bfhi(y.x); v0[2] += bflo(y.y); v0[3] += bfhi(y.y); v1[0] += bflo(y.z); v1[1] += bfhi(y.z); v1[2] += bflo(y.w); v1[3] += bfhi(y.w); }
;                         u32x4 w; w.x = pk2(v0[0], v0[1]); w.y = pk2(v0[2], v0[3]); w.z = pk2(v1[0], v1[1]); w.w = pk2(v1[2], v1[3]);
;                         *(u32x4*)((SECOND ? Mb : Y1) + (size_t)row * D + col) = w; }
	v_pk_add_f32 v[62:63], v[170:171], v[62:63]
	v_pk_add_f32 v[64:65], v[172:173], v[64:65]
	v_pk_mul_f32 v[58:59], v[58:59], s[98:99] op_sel_hi:[1,0]
	v_pk_mul_f32 v[60:61], v[60:61], s[98:99] op_sel_hi:[1,0]
	v_pk_mul_f32 v[62:63], v[62:63], s[98:99] op_sel_hi:[1,0]
	v_pk_mul_f32 v[64:65], v[64:65], s[98:99] op_sel_hi:[1,0]
	v_exp_f32_e32 v58, v58
	v_exp_f32_e32 v59, v59
	v_exp_f32_e32 v60, v60
	v_exp_f32_e32 v61, v61
	v_exp_f32_e32 v62, v62
	v_exp_f32_e32 v63, v63
	v_exp_f32_e32 v64, v64
	v_exp_f32_e32 v65, v65
	v_pk_add_f32 v[58:59], v[58:59], s[100:101] op_sel_hi:[1,0]
	v_pk_add_f32 v[60:61], v[60:61], s[100:101] op_sel_hi:[1,0]
	v_pk_add_f32 v[62:63], v[62:63], s[100:101] op_sel_hi:[1,0]
	v_pk_add_f32 v[64:65], v[64:65], s[100:101] op_sel_hi:[1,0]
	v_rcp_f32_e32 v58, v58
	v_rcp_f32_e32 v59, v59
	v_rcp_f32_e32 v60, v60
	v_rcp_f32_e32 v61, v61
	v_rcp_f32_e32 v62, v62
	v_rcp_f32_e32 v63, v63
	v_rcp_f32_e32 v64, v64
	v_rcp_f32_e32 v65, v65
	v_pk_mul_f32 v[102:103], v[102:103], v[58:59]
	v_pk_mul_f32 v[104:105], v[104:105], v[60:61]
	v_pk_mul_f32 v[98:99], v[98:99], v[62:63]
	v_pk_mul_f32 v[100:101], v[100:101], v[64:65]
	v_cvt_pk_bf16_f32 v46, v102, v103
	v_cvt_pk_bf16_f32 v47, v104, v105
	v_cvt_pk_bf16_f32 v48, v98, v99
	v_cvt_pk_bf16_f32 v49, v100, v101
	v_add_u32_e32 v200, 0x2f8000, v234
	global_load_dwordx4 v[200:203], v200, s[8:9]
	v_add_u32_e32 v184, 0x2f8000, v234
	global_load_dwordx4 v[184:187], v184, s[8:9] offset:256
	v_add_u32_e32 v236, 0x10000, v235
	global_store_dwordx4 v236, v[42:45], s[50:51]
	global_store_dwordx4 v236, v[46:49], s[50:51] offset:256
	s_waitcnt vmcnt(12)
	v_lshlrev_b32_e32 v58, 16, v188
	v_and_b32_e32 v59, 0xffff0000, v188
	v_lshlrev_b32_e32 v60, 16, v189
	v_and_b32_e32 v61, 0xffff0000, v189
	v_lshlrev_b32_e32 v62, 16, v190
	v_and_b32_e32 v63, 0xffff0000, v190
	v_lshlrev_b32_e32 v64, 16, v191
	v_and_b32_e32 v65, 0xffff0000, v191
	v_pk_add_f32 v[58:59], v[138:139], v[58:59]
	v_pk_add_f32 v[60:61], v[140:141], v[60:61]
	v_pk_add_f32 v[62:63], v[142:143], v[62:63]
	v_pk_add_f32 v[64:65], v[144:145], v[64:65]
	v_pk_mul_f32 v[58:59], v[58:59], s[98:99] op_sel_hi:[1,0]
	v_pk_mul_f32 v[60:61], v[60:61], s[98:99] op_sel_hi:[1,0]
	v_pk_mul_f32 v[62:63], v[62:63], s[98:99] op_sel_hi:[1,0]
	v_pk_mul_f32 v[64:65], v[64:65], s[98:99] op_sel_hi:[1,0]
	v_exp_f32_e32 v58, v58
	v_exp_f32_e32 v59, v59
	v_exp_f32_e32 v60, v60
	v_exp_f32_e32 v61, v61
	v_exp_f32_e32 v62, v62
	v_exp_f32_e32 v63, v63
	v_exp_f32_e32 v64, v64
	v_exp_f32_e32 v65, v65
	v_pk_add_f32 v[58:59], v[58:59], s[100:101] op_sel_hi:[1,0]
	v_pk_add_f32 v[60:61], v[60:61], s[100:101] op_sel_hi:[1,0]
	v_pk_add_f32 v[62:63], v[62:63], s[100:101] op_sel_hi:[1,0]
	v_pk_add_f32 v[64:65], v[64:65], s[100:101] op_sel_hi:[1,0]
	v_rcp_f32_e32 v58, v58
	v_rcp_f32_e32 v59, v59
	v_rcp_f32_e32 v60, v60
	v_rcp_f32_e32 v61, v61
	v_rcp_f32_e32 v62, v62
	v_rcp_f32_e32 v63, v63
	v_rcp_f32_e32 v64, v64
	v_rcp_f32_e32 v65, v65
	v_pk_mul_f32 v[94:95], v[94:95], v[58:59]
	v_pk_mul_f32 v[96:97], v[96:97], v[60:61]
	v_pk_mul_f32 v[90:91], v[90:91], v[62:63]
	v_pk_mul_f32 v[92:93], v[92:93], v[64:65]
	v_cvt_pk_bf16_f32 v42, v94, v95
	v_cvt_pk_bf16_f32 v43, v96, v97
	v_cvt_pk_bf16_f32 v44, v90, v91
	v_cvt_pk_bf16_f32 v45, v92, v93
	v_lshlrev_b32_e32 v58, 16, v174
	v_and_b32_e32 v59, 0xffff0000, v174
	v_lshlrev_b32_e32 v60, 16, v175
	v_and_b32_e32 v61, 0xffff0000, v175
	v_lshlrev_b32_e32 v62, 16, v176
	v_and_b32_e32 v63, 0xffff0000, v176
	v_lshlrev_b32_e32 v64, 16, v177
	v_and_b32_e32 v65, 0xffff0000, v177
	v_pk_add_f32 v[58:59], v[154:155], v[58:59]
	v_pk_add_f32 v[60:61], v[156:157], v[60:61]
	v_pk_add_f32 v[62:63], v[170:171], v[62:63]
	v_pk_add_f32 v[64:65], v[172:173], v[64:65]
	v_pk_mul_f32 v[58:59], v[58:59], s[98:99] op_sel_hi:[1,0]
	v_pk_mul_f32 v[60:61], v[60:61], s[98:99] op_sel_hi:[1,0]
	v_pk_mul_f32 v[62:63], v[62:63], s[98:99] op_sel_hi:[1,0]
	v_pk_mul_f32 v[64:65], v[64:65], s[98:99] op_sel_hi:[1,0]
	v_exp_f32_e32 v58, v58
	v_exp_f32_e32 v59, v59
	v_exp_f32_e32 v60, v60
	v_exp_f32_e32 v61, v61
	v_exp_f32_e32 v62, v62
	v_exp_f32_e32 v63, v63
	v_exp_f32_e32 v64, v64
	v_exp_f32_e32 v65, v65
	v_pk_add_f32 v[58:59], v[58:59], s[100:101] op_sel_hi:[1,0]
	v_pk_add_f32 v[60:61], v[60:61], s[100:101] op_sel_hi:[1,0]
	v_pk_add_f32 v[62:63], v[62:63], s[100:101] op_sel_hi:[1,0]
	v_pk_add_f32 v[64:65], v[64:65], s[100:101] op_sel_hi:[1,0]
	v_rcp_f32_e32 v58, v58
	v_rcp_f32_e32 v59, v59
	v_rcp_f32_e32 v60, v60
	v_rcp_f32_e32 v61, v61
	v_rcp_f32_e32 v62, v62
	v_rcp_f32_e32 v63, v63
	v_rcp_f32_e32 v64, v64
	v_rcp_f32_e32 v65, v65
	v_pk_mul_f32 v[86:87], v[86:87], v[58:59]
	v_pk_mul_f32 v[88:89], v[88:89], v[60:61]
	v_pk_mul_f32 v[82:83], v[82:83], v[62:63]
	v_pk_mul_f32 v[84:85], v[84:85], v[64:65]
	v_cvt_pk_bf16_f32 v46, v86, v87
	v_cvt_pk_bf16_f32 v47, v88, v89
	v_cvt_pk_bf16_f32 v48, v82, v83
	v_cvt_pk_bf16_f32 v49, v84, v85
	v_add_u32_e32 v188, 0x344000, v234
	global_load_dwordx4 v[188:191], v188, s[8:9]
	v_add_u32_e32 v174, 0x344000, v234
	global_load_dwordx4 v[174:177], v174, s[8:9] offset:256
	v_add_u32_e32 v236, 0x18000, v235
	global_store_dwordx4 v236, v[42:45], s[50:51]
	global_store_dwordx4 v236, v[46:49], s[50:51] offset:256
	s_waitcnt vmcnt(14)
; DI unsigned pk2(float lo, float hi) { unsigned r; asm("v_cvt_pk_bf16_f32 %0, %1, %2" : "=v"(r) : "v"(lo), "v"(hi)); return r; }
; DI float bflo(unsigned u) { return __uint_as_float(u << 16); }
; DI float bfhi(unsigned u) { return __uint_as_float(u & 0xffff0000u); }
; DI float fsigmoid(float x) { return frcp(1.0f + fexp2(-1.44269504f * x)); }
;     DI void operator()(const f32x4 (&acc)[2][2][4][2], const Unit& u, int wr, int wc, int fr, int fq) const {
;     ...
;                     for (int bj = 0; bj < 2; ++bj) { const int row = rowb + ai * HALF + (2 * mp + mm) * 16, col = col0 + bj * HALF;
;                         zg[mm][bj] = *(const u32x4*)(Zg + (size_t)row * INW + col);
;                         if (SECOND) yv[mm][bj] = *(const u32x4*)(Y1 + (size_t)row * D + col); }
;                 asm volatile("" ::: "memory");
; #pragma unroll
;                 for (int mm = 0; mm < 2; ++mm)
; #pragma unroll
;                     for (int bj = 0; bj < 2; ++bj) { const int m = 2 * mp + mm; const int row = rowb + ai * HALF + m * 16, col = col0 + bj * HALF;
;                         const u32x4 z = zg[mm][bj]; const f32x4 b0 = bb[bj][0], b1 = bb[bj][1];
;                         f32x4 g0, g1;
;                         g0[0] = fsigmoid(bflo(z.x) + b0[0]); g0[1] = fsigmoid(bfhi(z.x) + b0[1]); g0[2] = fsigmoid(bflo(z.y) + b0[2]); g0[3] = fsigmoid(bfhi(z.y) + b0[3]);
;                         g1[0] = fsigmoid(bflo(z.z) + b1[0]); g1[1] = fsigmoid(bfhi(z.z) + b1[1]); g1[2] = fsigmoid(bflo(z.w) + b1[2]); g1[3] = fsigmoid(bfhi(z.w) + b1[3]);
;                         f32x4 v0 = g0 * acc[ai][bj][m][0], v1 = g1 * acc[ai][bj][m][1];
;                         if (SECOND) { const u32x4 y = yv[mm][bj];
;                             v0[0] += bflo(y.x); v0[1] += bfhi(y.x); v0[2] += bflo(y.y); v0[3] += bfhi(y.y); v1[0] += bflo(y.z); v1[1] += bfhi(y.z); v1[2] += bflo(y.w); v1[3] += bfhi(y.w); }
;                         u32x4 w; w.x = pk2(v0[0], v0[1]); w.y = pk2(v0[2], v0[3]); w.z = pk2(v1[0], v1[1]); w.w = pk2(v1[2], v1[3]);
;                         *(u32x4*)((SECOND ? Mb : Y1) + (size_t)row * D + col) = w; }
	v_lshlrev_b32_e32 v58, 16, v206
	v_and_b32_e32 v59, 0xffff0000, v206
	v_lshlrev_b32_e32 v60, 16, v207
	v_and_b32_e32 v61, 0xffff0000, v207
	v_lshlrev_b32_e32 v62, 16, v208
	v_and_b32_e32 v63, 0xffff0000, v208
	v_lshlrev_b32_e32 v64, 16, v209
	v_and_b32_e32 v65, 0xffff0000, v209
	v_pk_add_f32 v[58:59], v[138:139], v[58:59]
	v_pk_add_f32 v[60:61], v[140:141], v[60:61]
	v_pk_add_f32 v[62:63], v[142:143], v[62:63]
	v_pk_add_f32 v[64:65], v[144:145], v[64:65]
	v_pk_mul_f32 v[58:59], v[58:59], s[98:99] op_sel_hi:[1,0]
	v_pk_mul_f32 v[60:61], v[60:61], s[98:99] op_sel_hi:[1,0]
	v_pk_mul_f32 v[62:63], v[62:63], s[98:99] op_sel_hi:[1,0]
	v_pk_mul_f32 v[64:65], v[64:65], s[98:99] op_sel_hi:[1,0]
	v_exp_f32_e32 v58, v58
	v_exp_f32_e32 v59, v59
	v_exp_f32_e32 v60, v60
	v_exp_f32_e32 v61, v61
	v_exp_f32_e32 v62, v62
	v_exp_f32_e32 v63, v63
	v_exp_f32_e32 v64, v64
	v_exp_f32_e32 v65, v65
	v_pk_add_f32 v[58:59], v[58:59], s[100:101] op_sel_hi:[1,0]
	v_pk_add_f32 v[60:61], v[60:61], s[100:101] op_sel_hi:[1,0]
	v_pk_add_f32 v[62:63], v[62:63], s[100:101] op_sel_hi:[1,0]
	v_pk_add_f32 v[64:65], v[64:65], s[100:101] op_sel_hi:[1,0]
	v_rcp_f32_e32 v58, v58
	v_rcp_f32_e32 v59, v59
	v_rcp_f32_e32 v60, v60
	v_rcp_f32_e32 v61, v61
	v_rcp_f32_e32 v62, v62
	v_rcp_f32_e32 v63, v63
	v_rcp_f32_e32 v64, v64
	v_rcp_f32_e32 v65, v65
	v_pk_mul_f32 v[78:79], v[78:79], v[58:59]
	v_pk_mul_f32 v[80:81], v[80:81], v[60:61]
	v_pk_mul_f32 v[74:75], v[74:75], v[62:63]
	v_pk_mul_f32 v[76:77], v[76:77], v[64:65]
	v_cvt_pk_bf16_f32 v42, v78, v79
	v_cvt_pk_bf16_f32 v43, v80, v81
	v_cvt_pk_bf16_f32 v44, v74, v75
	v_cvt_pk_bf16_f32 v45, v76, v77
	v_lshlrev_b32_e32 v58, 16, v210
	v_and_b32_e32 v59, 0xffff0000, v210
	v_lshlrev_b32_e32 v60, 16, v211
	v_and_b32_e32 v61, 0xffff0000, v211
	v_lshlrev_b32_e32 v62, 16, v212
	v_and_b32_e32 v63, 0xffff0000, v212
	v_lshlrev_b32_e32 v64, 16, v213
	v_and_b32_e32 v65, 0xffff0000, v213
	v_pk_add_f32 v[58:59], v[154:155], v[58:59]
	v_pk_add_f32 v[60:61], v[156:157], v[60:61]
	v_pk_add_f32 v[62:63], v[170:171], v[62:63]
	v_pk_add_f32 v[64:65], v[172:173], v[64:65]
	v_pk_mul_f32 v[58:59], v[58:59], s[98:99] op_sel_hi:[1,0]
	v_pk_mul_f32 v[60:61], v[60:61], s[98:99] op_sel_hi:[1,0]
	v_pk_mul_f32 v[62:63], v[62:63], s[98:99] op_sel_hi:[1,0]
	v_pk_mul_f32 v[64:65], v[64:65], s[98:99] op_sel_hi:[1,0]
	v_exp_f32_e32 v58, v58
	v_exp_f32_e32 v59, v59
	v_exp_f32_e32 v60, v60
	v_exp_f32_e32 v61, v61
	v_exp_f32_e32 v62, v62
	v_exp_f32_e32 v63, v63
	v_exp_f32_e32 v64, v64
	v_exp_f32_e32 v65, v65
	v_pk_add_f32 v[58:59], v[58:59], s[100:101] op_sel_hi:[1,0]
	v_pk_add_f32 v[60:61], v[60:61], s[100:101] op_sel_hi:[1,0]
	v_pk_add_f32 v[62:63], v[62:63], s[100:101] op_sel_hi:[1,0]
	v_pk_add_f32 v[64:65], v[64:65], s[100:101] op_sel_hi:[1,0]
	v_rcp_f32_e32 v58, v58
	v_rcp_f32_e32 v59, v59
	v_rcp_f32_e32 v60, v60
	v_rcp_f32_e32 v61, v61
	v_rcp_f32_e32 v62, v62
	v_rcp_f32_e32 v63, v63
	v_rcp_f32_e32 v64, v64
	v_rcp_f32_e32 v65, v65
	v_pk_mul_f32 v[70:71], v[70:71], v[58:59]
	v_pk_mul_f32 v[72:73], v[72:73], v[60:61]
	v_pk_mul_f32 v[66:67], v[66:67], v[62:63]
	v_pk_mul_f32 v[68:69], v[68:69], v[64:65]
	v_cvt_pk_bf16_f32 v46, v70, v71
	v_cvt_pk_bf16_f32 v47, v72, v73
	v_cvt_pk_bf16_f32 v48, v66, v67
	v_cvt_pk_bf16_f32 v49, v68, v69
	v_add_u32_e32 v236, 0x40000, v235
	global_store_dwordx4 v236, v[42:45], s[50:51]
	global_store_dwordx4 v236, v[46:49], s[50:51] offset:256
	s_waitcnt vmcnt(12)
	v_lshlrev_b32_e32 v58, 16, v214
	v_and_b32_e32 v59, 0xffff0000, v214
	v_lshlrev_b32_e32 v60, 16, v215
	v_and_b32_e32 v61, 0xffff0000, v215
	v_lshlrev_b32_e32 v62, 16, v216
	v_and_b32_e32 v63, 0xffff0000, v216
	v_lshlrev_b32_e32 v64, 16, v217
	v_and_b32_e32 v65, 0xffff0000, v217
	v_pk_add_f32 v[58:59], v[138:139], v[58:59]
	v_pk_add_f32 v[60:61], v[140:141], v[60:61]
	v_pk_add_f32 v[62:63], v[142:143], v[62:63]
	v_pk_add_f32 v[64:65], v[144:145], v[64:65]
	v_pk_mul_f32 v[58:59], v[58:59], s[98:99] op_sel_hi:[1,0]
	v_pk_mul_f32 v[60:61], v[60:61], s[98:99] op_sel_hi:[1,0]
	v_pk_mul_f32 v[62:63], v[62:63], s[98:99] op_sel_hi:[1,0]
	v_pk_mul_f32 v[64:65], v[64:65], s[98:99] op_sel_hi:[1,0]
	v_exp_f32_e32 v58, v58
	v_exp_f32_e32 v59, v59
	v_exp_f32_e32 v60, v60
	v_exp_f32_e32 v61, v61
	v_exp_f32_e32 v62, v62
	v_exp_f32_e32 v63, v63
	v_exp_f32_e32 v64, v64
	v_exp_f32_e32 v65, v65
	v_pk_add_f32 v[58:59], v[58:59], s[100:101] op_sel_hi:[1,0]
	v_pk_add_f32 v[60:61], v[60:61], s[100:101] op_sel_hi:[1,0]
	v_pk_add_f32 v[62:63], v[62:63], s[100:101] op_sel_hi:[1,0]
	v_pk_add_f32 v[64:65], v[64:65], s[100:101] op_sel_hi:[1,0]
	v_rcp_f32_e32 v58, v58
	v_rcp_f32_e32 v59, v59
	v_rcp_f32_e32 v60, v60
	v_rcp_f32_e32 v61, v61
	v_rcp_f32_e32 v62, v62
	v_rcp_f32_e32 v63, v63
	v_rcp_f32_e32 v64, v64
	v_rcp_f32_e32 v65, v65
	v_pk_mul_f32 v[54:55], v[54:55], v[58:59]
	v_pk_mul_f32 v[56:57], v[56:57], v[60:61]
	v_pk_mul_f32 v[50:51], v[50:51], v[62:63]
	v_pk_mul_f32 v[52:53], v[52:53], v[64:65]
	v_cvt_pk_bf16_f32 v42, v54, v55
	v_cvt_pk_bf16_f32 v43, v56, v57
	v_cvt_pk_bf16_f32 v44, v50, v51
	v_cvt_pk_bf16_f32 v45, v52, v53
	v_lshlrev_b32_e32 v58, 16, v218
	v_and_b32_e32 v59, 0xffff0000, v218
	v_lshlrev_b32_e32 v60, 16, v219
	v_and_b32_e32 v61, 0xffff0000, v219
	v_lshlrev_b32_e32 v62, 16, v220
	v_and_b32_e32 v63, 0xffff0000, v220
	v_lshlrev_b32_e32 v64, 16, v221
	v_and_b32_e32 v65, 0xffff0000, v221
	v_pk_add_f32 v[58:59], v[154:155], v[58:59]
	v_pk_add_f32 v[60:61], v[156:157], v[60:61]
	v_pk_add_f32 v[62:63], v[170:171], v[62:63]
	v_pk_add_f32 v[64:65], v[172:173], v[64:65]
	v_pk_mul_f32 v[58:59], v[58:59], s[98:99] op_sel_hi:[1,0]
	v_pk_mul_f32 v[60:61], v[60:61], s[98:99] op_sel_hi:[1,0]
	v_pk_mul_f32 v[62:63], v[62:63], s[98:99] op_sel_hi:[1,0]
	v_pk_mul_f32 v[64:65], v[64:65], s[98:99] op_sel_hi:[1,0]
	v_exp_f32_e32 v58, v58
	v_exp_f32_e32 v59, v59
	v_exp_f32_e32 v60, v60
	v_exp_f32_e32 v61, v61
	v_exp_f32_e32 v62, v62
	v_exp_f32_e32 v63, v63
	v_exp_f32_e32 v64, v64
	v_exp_f32_e32 v65, v65
	v_pk_add_f32 v[58:59], v[58:59], s[100:101] op_sel_hi:[1,0]
	v_pk_add_f32 v[60:61], v[60:61], s[100:101] op_sel_hi:[1,0]
	v_pk_add_f32 v[62:63], v[62:63], s[100:101] op_sel_hi:[1,0]
	v_pk_add_f32 v[64:65], v[64:65], s[100:101] op_sel_hi:[1,0]
	v_rcp_f32_e32 v58, v58
	v_rcp_f32_e32 v59, v59
	v_rcp_f32_e32 v60, v60
	v_rcp_f32_e32 v61, v61
	v_rcp_f32_e32 v62, v62
	v_rcp_f32_e32 v63, v63
	v_rcp_f32_e32 v64, v64
	v_rcp_f32_e32 v65, v65
	v_pk_mul_f32 v[38:39], v[38:39], v[58:59]
	v_pk_mul_f32 v[40:41], v[40:41], v[60:61]
	v_pk_mul_f32 v[34:35], v[34:35], v[62:63]
	v_pk_mul_f32 v[36:37], v[36:37], v[64:65]
	v_cvt_pk_bf16_f32 v46, v38, v39
	v_cvt_pk_bf16_f32 v47, v40, v41
	v_cvt_pk_bf16_f32 v48, v34, v35
	v_cvt_pk_bf16_f32 v49, v36, v37
	v_add_u32_e32 v236, 0x48000, v235
	global_store_dwordx4 v236, v[42:45], s[50:51]
	global_store_dwordx4 v236, v[46:49], s[50:51] offset:256
	s_waitcnt vmcnt(10)
; DI float bflo(unsigned u) { return __uint_as_float(u << 16); }
; template <class Epi>
; DI void gemm_phase(LAS unsigned char* lds, const Gemm g, const StaticOrder& S, const Epi& E) {
;     ...
;         if (!has_next) break;
; #pragma unroll
;         for (int a = 0; a < 2; ++a)
; #pragma unroll
;             for (int b = 0; b < 2; ++b)
; #pragma unroll
;                 for (int m = 0; m < 4; ++m)
; #pragma unroll
;                     for (int n = 0; n < 2; ++n) acc[a][b][m][n] = (f32x4){0.f, 0.f, 0.f, 0.f};
;         cur = nxt; cA = nA; cB = nB; ++ui;
;         if (wr == 1) PG8_BAR;
;     DI void operator()(const f32x4 (&acc)[2][2][4][2], const Unit& u, int wr, int wc, int fr, int fq) const {
;     ...
;                     for (int bj = 0; bj < 2; ++bj) { const int row = rowb + ai * HALF + (2 * mp + mm) * 16, col = col0 + bj * HALF;
;                         zg[mm][bj] = *(const u32x4*)(Zg + (size_t)row * INW + col);
;                         if (SECOND) yv[mm][bj] = *(const u32x4*)(Y1 + (size_t)row * D + col); }
;                 asm volatile("" ::: "memory");
; #pragma unroll
;                 for (int mm = 0; mm < 2; ++mm)
; #pragma unroll
;                     for (int bj = 0; bj < 2; ++bj) { const int m = 2 * mp + mm; const int row = rowb + ai * HALF + m * 16, col = col0 + bj * HALF;
;                         const u32x4 z = zg[mm][bj]; const f32x4 b0 = bb[bj][0], b1 = bb[bj][1];
;                         f32x4 g0, g1;
;                         g0[0] = fsigmoid(bflo(z.x) + b0[0]); g0[1] = fsigmoid(bfhi(z.x) + b0[1]); g0[2] = fsigmoid(bflo(z.y) + b0[2]); g0[3] = fsigmoid(bfhi(z.y) + b0[3]);
;                         g1[0] = fsigmoid(bflo(z.z) + b1[0]); g1[1] = fsigmoid(bfhi(z.z) + b1[1]); g1[2] = fsigmoid(bflo(z.w) + b1[2]); g1[3] = fsigmoid(bfhi(z.w) + b1[3]);
;                         f32x4 v0 = g0 * acc[ai][bj][m][0], v1 = g1 * acc[ai][bj][m][1];
;                         if (SECOND) { const u32x4 y = yv[mm][bj];
;                             v0[0] += bflo(y.x); v0[1] += bfhi(y.x); v0[2] += bflo(y.y); v0[3] += bfhi(y.y); v1[0] += bflo(y.z); v1[1] += bfhi(y.z); v1[2] += bflo(y.w); v1[3] += bfhi(y.w); }
;                         u32x4 w; w.x = pk2(v0[0], v0[1]); w.y = pk2(v0[2], v0[3]); w.z = pk2(v1[0], v1[1]); w.w = pk2(v1[2], v1[3]);
;                         *(u32x4*)((SECOND ? Mb : Y1) + (size_t)row * D + col) = w; }
	v_lshlrev_b32_e32 v58, 16, v200
	v_and_b32_e32 v59, 0xffff0000, v200
	v_lshlrev_b32_e32 v60, 16, v201
	v_and_b32_e32 v61, 0xffff0000, v201
	v_lshlrev_b32_e32 v62, 16, v202
	v_and_b32_e32 v63, 0xffff0000, v202
	v_lshlrev_b32_e32 v64, 16, v203
	v_and_b32_e32 v65, 0xffff0000, v203
	v_pk_add_f32 v[58:59], v[138:139], v[58:59]
	v_pk_add_f32 v[60:61], v[140:141], v[60:61]
	v_pk_add_f32 v[62:63], v[142:143], v[62:63]
	v_pk_add_f32 v[64:65], v[144:145], v[64:65]
	v_pk_mul_f32 v[58:59], v[58:59], s[98:99] op_sel_hi:[1,0]
	v_pk_mul_f32 v[60:61], v[60:61], s[98:99] op_sel_hi:[1,0]
	v_pk_mul_f32 v[62:63], v[62:63], s[98:99] op_sel_hi:[1,0]
	v_pk_mul_f32 v[64:65], v[64:65], s[98:99] op_sel_hi:[1,0]
	v_exp_f32_e32 v58, v58
	v_exp_f32_e32 v59, v59
	v_exp_f32_e32 v60, v60
	v_exp_f32_e32 v61, v61
	v_exp_f32_e32 v62, v62
	v_exp_f32_e32 v63, v63
	v_exp_f32_e32 v64, v64
	v_exp_f32_e32 v65, v65
	v_pk_add_f32 v[58:59], v[58:59], s[100:101] op_sel_hi:[1,0]
	v_pk_add_f32 v[60:61], v[60:61], s[100:101] op_sel_hi:[1,0]
	v_pk_add_f32 v[62:63], v[62:63], s[100:101] op_sel_hi:[1,0]
	v_pk_add_f32 v[64:65], v[64:65], s[100:101] op_sel_hi:[1,0]
	v_rcp_f32_e32 v58, v58
	v_rcp_f32_e32 v59, v59
	v_rcp_f32_e32 v60, v60
	v_rcp_f32_e32 v61, v61
	v_rcp_f32_e32 v62, v62
	v_rcp_f32_e32 v63, v63
	v_rcp_f32_e32 v64, v64
	v_rcp_f32_e32 v65, v65
	v_pk_mul_f32 v[30:31], v[30:31], v[58:59]
	v_pk_mul_f32 v[32:33], v[32:33], v[60:61]
	v_pk_mul_f32 v[26:27], v[26:27], v[62:63]
	v_pk_mul_f32 v[28:29], v[28:29], v[64:65]
	v_cvt_pk_bf16_f32 v42, v30, v31
	v_cvt_pk_bf16_f32 v43, v32, v33
	v_cvt_pk_bf16_f32 v44, v26, v27
	v_cvt_pk_bf16_f32 v45, v28, v29
	v_lshlrev_b32_e32 v58, 16, v184
	v_and_b32_e32 v59, 0xffff0000, v184
	v_lshlrev_b32_e32 v60, 16, v185
	v_and_b32_e32 v61, 0xffff0000, v185
	v_lshlrev_b32_e32 v62, 16, v186
	v_and_b32_e32 v63, 0xffff0000, v186
	v_lshlrev_b32_e32 v64, 16, v187
	v_and_b32_e32 v65, 0xffff0000, v187
	v_pk_add_f32 v[58:59], v[154:155], v[58:59]
	v_pk_add_f32 v[60:61], v[156:157], v[60:61]
	v_pk_add_f32 v[62:63], v[170:171], v[62:63]
	v_pk_add_f32 v[64:65], v[172:173], v[64:65]
	v_pk_mul_f32 v[58:59], v[58:59], s[98:99] op_sel_hi:[1,0]
	v_pk_mul_f32 v[60:61], v[60:61], s[98:99] op_sel_hi:[1,0]
	v_pk_mul_f32 v[62:63], v[62:63], s[98:99] op_sel_hi:[1,0]
	v_pk_mul_f32 v[64:65], v[64:65], s[98:99] op_sel_hi:[1,0]
	v_exp_f32_e32 v58, v58
	v_exp_f32_e32 v59, v59
	v_exp_f32_e32 v60, v60
	v_exp_f32_e32 v61, v61
	v_exp_f32_e32 v62, v62
	v_exp_f32_e32 v63, v63
	v_exp_f32_e32 v64, v64
	v_exp_f32_e32 v65, v65
	v_pk_add_f32 v[58:59], v[58:59], s[100:101] op_sel_hi:[1,0]
	v_pk_add_f32 v[60:61], v[60:61], s[100:101] op_sel_hi:[1,0]
	v_pk_add_f32 v[62:63], v[62:63], s[100:101] op_sel_hi:[1,0]
	v_pk_add_f32 v[64:65], v[64:65], s[100:101] op_sel_hi:[1,0]
	v_rcp_f32_e32 v58, v58
	v_rcp_f32_e32 v59, v59
	v_rcp_f32_e32 v60, v60
	v_rcp_f32_e32 v61, v61
	v_rcp_f32_e32 v62, v62
	v_rcp_f32_e32 v63, v63
	v_rcp_f32_e32 v64, v64
	v_rcp_f32_e32 v65, v65
	v_pk_mul_f32 v[22:23], v[22:23], v[58:59]
	v_pk_mul_f32 v[24:25], v[24:25], v[60:61]
	v_pk_mul_f32 v[18:19], v[18:19], v[62:63]
	v_pk_mul_f32 v[20:21], v[20:21], v[64:65]
	v_cvt_pk_bf16_f32 v46, v22, v23
	v_cvt_pk_bf16_f32 v47, v24, v25
	v_cvt_pk_bf16_f32 v48, v18, v19
	v_cvt_pk_bf16_f32 v49, v20, v21
	v_add_u32_e32 v236, 0x50000, v235
	global_store_dwordx4 v236, v[42:45], s[50:51]
	global_store_dwordx4 v236, v[46:49], s[50:51] offset:256
	s_waitcnt vmcnt(8)
	v_lshlrev_b32_e32 v58, 16, v188
	v_and_b32_e32 v59, 0xffff0000, v188
	v_lshlrev_b32_e32 v60, 16, v189
	v_and_b32_e32 v61, 0xffff0000, v189
	v_lshlrev_b32_e32 v62, 16, v190
	v_and_b32_e32 v63, 0xffff0000, v190
	v_lshlrev_b32_e32 v64, 16, v191
	v_and_b32_e32 v65, 0xffff0000, v191
	v_pk_add_f32 v[58:59], v[138:139], v[58:59]
	v_pk_add_f32 v[60:61], v[140:141], v[60:61]
	v_pk_add_f32 v[62:63], v[142:143], v[62:63]
	v_pk_add_f32 v[64:65], v[144:145], v[64:65]
	v_pk_mul_f32 v[58:59], v[58:59], s[98:99] op_sel_hi:[1,0]
	v_pk_mul_f32 v[60:61], v[60:61], s[98:99] op_sel_hi:[1,0]
	v_pk_mul_f32 v[62:63], v[62:63], s[98:99] op_sel_hi:[1,0]
	v_pk_mul_f32 v[64:65], v[64:65], s[98:99] op_sel_hi:[1,0]
	v_exp_f32_e32 v58, v58
	v_exp_f32_e32 v59, v59
	v_exp_f32_e32 v60, v60
	v_exp_f32_e32 v61, v61
	v_exp_f32_e32 v62, v62
	v_exp_f32_e32 v63, v63
	v_exp_f32_e32 v64, v64
	v_exp_f32_e32 v65, v65
	v_pk_add_f32 v[58:59], v[58:59], s[100:101] op_sel_hi:[1,0]
	v_pk_add_f32 v[60:61], v[60:61], s[100:101] op_sel_hi:[1,0]
	v_pk_add_f32 v[62:63], v[62:63], s[100:101] op_sel_hi:[1,0]
	v_pk_add_f32 v[64:65], v[64:65], s[100:101] op_sel_hi:[1,0]
	v_rcp_f32_e32 v58, v58
	v_rcp_f32_e32 v59, v59
	v_rcp_f32_e32 v60, v60
	v_rcp_f32_e32 v61, v61
	v_rcp_f32_e32 v62, v62
	v_rcp_f32_e32 v63, v63
	v_rcp_f32_e32 v64, v64
	v_rcp_f32_e32 v65, v65
	v_pk_mul_f32 v[14:15], v[14:15], v[58:59]
	v_pk_mul_f32 v[16:17], v[16:17], v[60:61]
	v_pk_mul_f32 v[10:11], v[10:11], v[62:63]
	v_pk_mul_f32 v[12:13], v[12:13], v[64:65]
	v_cvt_pk_bf16_f32 v42, v14, v15
	v_cvt_pk_bf16_f32 v43, v16, v17
	v_cvt_pk_bf16_f32 v44, v10, v11
	v_cvt_pk_bf16_f32 v45, v12, v13
	v_lshlrev_b32_e32 v58, 16, v174
	v_and_b32_e32 v59, 0xffff0000, v174
	v_lshlrev_b32_e32 v60, 16, v175
	v_and_b32_e32 v61, 0xffff0000, v175
	v_lshlrev_b32_e32 v62, 16, v176
	v_and_b32_e32 v63, 0xffff0000, v176
	v_lshlrev_b32_e32 v64, 16, v177
	v_and_b32_e32 v65, 0xffff0000, v177
	v_pk_add_f32 v[58:59], v[154:155], v[58:59]
	v_pk_add_f32 v[60:61], v[156:157], v[60:61]
	v_pk_add_f32 v[62:63], v[170:171], v[62:63]
	v_pk_add_f32 v[64:65], v[172:173], v[64:65]
	v_pk_mul_f32 v[58:59], v[58:59], s[98:99] op_sel_hi:[1,0]
	v_pk_mul_f32 v[60:61], v[60:61], s[98:99] op_sel_hi:[1,0]
	v_pk_mul_f32 v[62:63], v[62:63], s[98:99] op_sel_hi:[1,0]
	v_pk_mul_f32 v[64:65], v[64:65], s[98:99] op_sel_hi:[1,0]
	v_exp_f32_e32 v58, v58
	v_exp_f32_e32 v59, v59
	v_exp_f32_e32 v60, v60
	v_exp_f32_e32 v61, v61
	v_exp_f32_e32 v62, v62
	v_exp_f32_e32 v63, v63
	v_exp_f32_e32 v64, v64
	v_exp_f32_e32 v65, v65
	v_pk_add_f32 v[58:59], v[58:59], s[100:101] op_sel_hi:[1,0]
	v_pk_add_f32 v[60:61], v[60:61], s[100:101] op_sel_hi:[1,0]
	v_pk_add_f32 v[62:63], v[62:63], s[100:101] op_sel_hi:[1,0]
	v_pk_add_f32 v[64:65], v[64:65], s[100:101] op_sel_hi:[1,0]
	v_rcp_f32_e32 v58, v58
	v_rcp_f32_e32 v59, v59
	v_rcp_f32_e32 v60, v60
	v_rcp_f32_e32 v61, v61
	v_rcp_f32_e32 v62, v62
	v_rcp_f32_e32 v63, v63
	v_rcp_f32_e32 v64, v64
	v_rcp_f32_e32 v65, v65
	v_pk_mul_f32 v[6:7], v[6:7], v[58:59]
	v_pk_mul_f32 v[8:9], v[8:9], v[60:61]
	v_pk_mul_f32 v[2:3], v[2:3], v[62:63]
	v_pk_mul_f32 v[4:5], v[4:5], v[64:65]
	v_cvt_pk_bf16_f32 v46, v6, v7
	v_cvt_pk_bf16_f32 v47, v8, v9
	v_cvt_pk_bf16_f32 v48, v2, v3
	v_cvt_pk_bf16_f32 v49, v4, v5
	v_add_u32_e32 v236, 0x58000, v235
	global_store_dwordx4 v236, v[42:45], s[50:51]
	global_store_dwordx4 v236, v[46:49], s[50:51] offset:256
	s_mov_b64 s[62:63], -1
	s_andn2_b64 vcc, exec, s[4:5]
	s_cbranch_vccnz .LBB0_507
	s_andn2_b64 vcc, exec, s[6:7]
	s_cbranch_vccnz .LBB0_506
	s_barrier
	s_branch .LBB0_506
